# mode-1: wave sums of a sub-block's 8 steps taken together through an LDS transpose
# speedup vs baseline: 1.0079x; 1.0060x over previous
; #define LAS __attribute__((address_space(3)))
; template <int MODE> __device__ __forceinline__ void rwkv_item(const Params& P, int e, int c, int h, LAS float* slab, int lane) {
;     unsigned char* ws = P.ws;
;     const bf16* PA = (const bf16*)(ws + OFF_PA);
;     const float* DEC = (const float*)(ws + OFF_DEC); const bf16* A16 = (const bf16*)(ws + OFF_A16); const bf16* G16 = (const bf16*)(ws + OFF_G16);
;     const bf16* V16 = (const bf16*)(ws + (e == 0 ? OFF_VF : OFF_V16));
;     float* MCM = (float*)(ws + OFF_MCM); float* MCC = (float*)(ws + OFF_MCC); bf16* MIX = (bf16*)(ws + OFF_MIXE);
;     const int ch = h * 64 + lane;
;     const float mu_r = P.in[I_AMU][(size_t)e * DINA + ch], mu_k = P.in[I_AMU][(size_t)e * DINA + 512 + ch];
;     const float kkw = P.in[I_AKK][e * 512 + ch], ka = P.in[I_AKA][e * 512 + ch], rk = P.in[I_ARK][e * 512 + ch];
;     const float lnw = P.in[I_ALNW][e * 512 + ch], lnb = P.in[I_ALNB][e * 512 + ch];
; template <int MODE> __device__ __forceinline__ void stage_rwkv_scan(const Params& P, int e, LAS unsigned char* lds) {
;     int tid = threadIdx.x; asm volatile("" : "+v"(tid)); const int lane = tid & 63, wave = __builtin_amdgcn_readfirstlane(tid >> 6);
;     LAS float* slab = (LAS float*)(lds + wave * 16384);
;     const int gw = blockIdx.x * NWAVES + wave, ngw = gridDim.x * NWAVES;
;     for (int it = gw; it < RNCH * 8; it += ngw) rwkv_item<MODE>(P, e, it >> 3, it & 7, slab, lane);
.LBB0_202:
	s_andn2_b64 vcc, exec, s[0:1]
	s_cbranch_vccnz .LBB0_213
	v_mov_b32_e32 v0, v211
	s_nop 0
	v_readfirstlane_b32 s0, v0
	s_ashr_i32 s0, s0, 6
	s_add_i32 s2, s0, s55
	s_cmpk_gt_i32 s2, 0x7ff
	s_cbranch_scc1 .LBB0_213
	s_lshl_b32 s0, s0, 14
	s_add_i32 s3, s0, 0
	s_load_dwordx2 s[0:1], s[30:31], 0x38
	s_load_dwordx8 s[12:19], s[30:31], 0x68
	s_load_dwordx2 s[8:9], s[30:31], 0x88
	s_waitcnt lgkmcnt(0)
	s_add_u32 s4, s72, 0xd880000
	s_addc_u32 s5, s73, 0
	s_add_u32 s6, s72, 0x12880000
	s_addc_u32 s7, s73, 0
	v_readlane_b32 s10, v255, 5
	s_add_u32 s26, s0, s10
	v_readlane_b32 s0, v255, 4
	s_addc_u32 s27, s1, s0
	s_add_u32 s46, s72, 0xb880000
	s_addc_u32 s47, s73, 0
	s_add_u32 s50, s72, 0xf880000
	s_addc_u32 s51, s73, 0
	v_readlane_b32 s0, v255, 3
	s_add_u32 s66, s72, s0
	s_addc_u32 s67, s73, 0
	s_add_u32 s70, s72, 0x10880000
	s_addc_u32 s71, s73, 0
	v_readlane_b32 s52, v254, 55
	v_readlane_b32 s53, v254, 56
	v_and_b32_e32 v64, 63, v0
	v_lshl_add_u32 v109, v64, 2, s3
	s_mov_b64 s[72:73], s[8:9]
	v_lshrrev_b32_e32 v114, 3, v64
	v_and_b32_e32 v115, 7, v64
	v_lshlrev_b32_e32 v175, 11, v114
	v_lshl_add_u32 v175, v115, 5, v175
	v_add_u32_e32 v175, s3, v175
	s_lshr_b32 s8, s3, 8
	s_add_i32 s8, s8, 0x20100
	v_lshl_add_u32 v208, v114, 2, s8
	v_mov_b32_e32 v209, s8

; #define LAS __attribute__((address_space(3)))
; __device__ __forceinline__ float frsq(float x) { return __builtin_amdgcn_rsqf(x); }
; template <int MODE> __device__ __forceinline__ void rwkv_item(const Params& P, int e, int c, int h, LAS float* slab, int lane) {
;     ...
; #pragma unroll
;         for (int s = 0; s < SB; ++s) {
;             const float r = r1[s + 1] + (r1[s] - r1[s + 1]) * mu_r, k = k1[s + 1] + (k1[s] - k1[s + 1]) * mu_k, a = aa[s];
;             float kk = k * kkw;
;             const float ss = wave_sum(kk * kk);
;             kk *= frsq(fmaxf(ss, 1e-24f));
;             const float b = kk * a, kp = k * (1.f + (a - 1.f) * ka);
;             LAS float* st = slab + s * 512;
;             st[lane] = dd[s]; st[64 + lane] = kk; st[128 + lane] = b; st[192 + lane] = kp; st[256 + lane] = r; st[320 + lane] = vv[s];
;             if (MODE == 1) { st[384 + lane] = wave_sum(r * kp * rk); st[448 + lane] = gg[s]; }
.Lm1_prep:
	v_lshlrev_b32_e32 v73, 16, v73
	v_lshlrev_b32_e32 v65, 16, v65
	v_lshlrev_b32_e32 v74, 16, v74
	v_lshlrev_b32_e32 v66, 16, v66
	v_lshlrev_b32_e32 v75, 16, v75
	v_lshlrev_b32_e32 v67, 16, v67
	v_lshlrev_b32_e32 v76, 16, v76
	v_lshlrev_b32_e32 v68, 16, v68
	v_lshlrev_b32_e32 v77, 16, v77
	v_lshlrev_b32_e32 v69, 16, v69
	v_lshlrev_b32_e32 v78, 16, v78
	v_lshlrev_b32_e32 v70, 16, v70
	v_lshlrev_b32_e32 v79, 16, v79
	v_lshlrev_b32_e32 v71, 16, v71
	v_lshlrev_b32_e32 v80, 16, v80
	v_lshlrev_b32_e32 v72, 16, v72
	v_sub_f32_e32 v136, v106, v73
	v_sub_f32_e32 v176, v105, v65
	v_fma_f32 v136, v116, v136, v73
	v_fma_f32 v176, v111, v176, v65
	v_lshlrev_b32_e32 v97, 16, v97
	v_mul_f32_e32 v144, v117, v136
	v_add_f32_e32 v127, -1.0, v97
	v_mul_f32_e32 v124, v144, v144
	v_fma_f32 v127, v118, v127, 1.0
	ds_write_b32 v109, v124
	v_mul_f32_e32 v136, v136, v127
	v_mul_f32_e32 v125, v176, v136
	v_mul_f32_e32 v125, v119, v125
	ds_write_b32 v109, v125 offset:1536
	v_sub_f32_e32 v137, v73, v74
	v_sub_f32_e32 v177, v65, v66
	v_fma_f32 v137, v116, v137, v74
	v_fma_f32 v177, v111, v177, v66
	v_lshlrev_b32_e32 v98, 16, v98
	v_mul_f32_e32 v145, v117, v137
	v_add_f32_e32 v127, -1.0, v98
	v_mul_f32_e32 v124, v145, v145
	v_fma_f32 v127, v118, v127, 1.0
	ds_write_b32 v109, v124 offset:2048
	v_mul_f32_e32 v137, v137, v127
	v_mul_f32_e32 v125, v177, v137
	v_mul_f32_e32 v125, v119, v125
	ds_write_b32 v109, v125 offset:3584
	v_sub_f32_e32 v138, v74, v75
	v_sub_f32_e32 v178, v66, v67
	v_fma_f32 v138, v116, v138, v75
	v_fma_f32 v178, v111, v178, v67
	v_lshlrev_b32_e32 v99, 16, v99
	v_mul_f32_e32 v146, v117, v138
	v_add_f32_e32 v127, -1.0, v99
	v_mul_f32_e32 v124, v146, v146
	v_fma_f32 v127, v118, v127, 1.0
	ds_write_b32 v109, v124 offset:4096
	v_mul_f32_e32 v138, v138, v127
	v_mul_f32_e32 v125, v178, v138
	v_mul_f32_e32 v125, v119, v125
	ds_write_b32 v109, v125 offset:5632
	v_sub_f32_e32 v139, v75, v76
	v_sub_f32_e32 v179, v67, v68
	v_fma_f32 v139, v116, v139, v76
	v_fma_f32 v179, v111, v179, v68
	v_lshlrev_b32_e32 v100, 16, v100
	v_mul_f32_e32 v147, v117, v139
	v_add_f32_e32 v127, -1.0, v100
	v_mul_f32_e32 v124, v147, v147
	v_fma_f32 v127, v118, v127, 1.0
	ds_write_b32 v109, v124 offset:6144
	v_mul_f32_e32 v139, v139, v127
	v_mul_f32_e32 v125, v179, v139
	v_mul_f32_e32 v125, v119, v125
	ds_write_b32 v109, v125 offset:7680
	v_sub_f32_e32 v140, v76, v77
	v_sub_f32_e32 v180, v68, v69
	v_fma_f32 v140, v116, v140, v77
	v_fma_f32 v180, v111, v180, v69
	v_lshlrev_b32_e32 v101, 16, v101
	v_mul_f32_e32 v148, v117, v140
	v_add_f32_e32 v127, -1.0, v101
	v_mul_f32_e32 v124, v148, v148
	v_fma_f32 v127, v118, v127, 1.0
	ds_write_b32 v109, v124 offset:8192
	v_mul_f32_e32 v140, v140, v127
	v_mul_f32_e32 v125, v180, v140
	v_mul_f32_e32 v125, v119, v125
	ds_write_b32 v109, v125 offset:9728
	v_sub_f32_e32 v141, v77, v78
	v_sub_f32_e32 v181, v69, v70
	v_fma_f32 v141, v116, v141, v78
	v_fma_f32 v181, v111, v181, v70
	v_lshlrev_b32_e32 v102, 16, v102
	v_mul_f32_e32 v149, v117, v141
	v_add_f32_e32 v127, -1.0, v102
	v_mul_f32_e32 v124, v149, v149
	v_fma_f32 v127, v118, v127, 1.0
	ds_write_b32 v109, v124 offset:10240
	v_mul_f32_e32 v141, v141, v127
	v_mul_f32_e32 v125, v181, v141
	v_mul_f32_e32 v125, v119, v125
	ds_write_b32 v109, v125 offset:11776
	v_sub_f32_e32 v142, v78, v79
	v_sub_f32_e32 v182, v70, v71
	v_fma_f32 v142, v116, v142, v79
	v_fma_f32 v182, v111, v182, v71
	v_lshlrev_b32_e32 v103, 16, v103
	v_mul_f32_e32 v150, v117, v142
	v_add_f32_e32 v127, -1.0, v103
	v_mul_f32_e32 v124, v150, v150
	v_fma_f32 v127, v118, v127, 1.0
	ds_write_b32 v109, v124 offset:12288
	v_mul_f32_e32 v142, v142, v127
	v_mul_f32_e32 v125, v182, v142
	v_mul_f32_e32 v125, v119, v125
	ds_write_b32 v109, v125 offset:13824
	v_sub_f32_e32 v143, v79, v80
	v_sub_f32_e32 v183, v71, v72
	v_fma_f32 v143, v116, v143, v80
	v_fma_f32 v183, v111, v183, v72
	v_lshlrev_b32_e32 v104, 16, v104
	v_mul_f32_e32 v151, v117, v143
	v_add_f32_e32 v127, -1.0, v104
	v_mul_f32_e32 v124, v151, v151
	v_fma_f32 v127, v118, v127, 1.0
	ds_write_b32 v109, v124 offset:14336
	v_mul_f32_e32 v143, v143, v127
	v_mul_f32_e32 v125, v183, v143
	v_mul_f32_e32 v125, v119, v125
	ds_write_b32 v109, v125 offset:15872
	v_mov_b32_e32 v106, v80
	v_mov_b32_e32 v105, v72
	s_waitcnt lgkmcnt(0)
	ds_read_b128 v[192:195], v175
	ds_read_b128 v[196:199], v175 offset:16
	ds_read_b128 v[128:131], v175 offset:1536
	ds_read_b128 v[132:135], v175 offset:1552
	s_waitcnt lgkmcnt(2)
	v_add_f32_e32 v192, v192, v193
	v_add_f32_e32 v194, v194, v195
	v_add_f32_e32 v196, v196, v197
	v_add_f32_e32 v198, v198, v199
	v_add_f32_e32 v192, v192, v194
	v_add_f32_e32 v196, v196, v198
	v_add_f32_e32 v192, v192, v196
	s_waitcnt lgkmcnt(0)
	v_add_f32_e32 v128, v128, v129
	v_add_f32_e32 v130, v130, v131
	v_add_f32_e32 v132, v132, v133
	v_add_f32_e32 v134, v134, v135
	v_add_f32_e32 v128, v128, v130
	v_add_f32_e32 v132, v132, v134
	v_add_f32_e32 v128, v128, v132
	s_nop 0
	v_add_f32_dpp v192, v192, v192 quad_perm:[1,0,3,2] row_mask:0xf bank_mask:0xf bound_ctrl:1
	v_add_f32_dpp v128, v128, v128 quad_perm:[1,0,3,2] row_mask:0xf bank_mask:0xf bound_ctrl:1
	s_nop 0
	v_add_f32_dpp v192, v192, v192 quad_perm:[2,3,0,1] row_mask:0xf bank_mask:0xf bound_ctrl:1
	v_add_f32_dpp v128, v128, v128 quad_perm:[2,3,0,1] row_mask:0xf bank_mask:0xf bound_ctrl:1
	s_nop 0
	v_add_f32_dpp v192, v192, v192 row_half_mirror row_mask:0xf bank_mask:0xf bound_ctrl:1
	v_add_f32_dpp v128, v128, v128 row_half_mirror row_mask:0xf bank_mask:0xf bound_ctrl:1
	ds_write_b32 v208, v192
	ds_write_b32 v208, v128 offset:32
	s_waitcnt lgkmcnt(0)
; #define LAS __attribute__((address_space(3)))
; __device__ __forceinline__ float frsq(float x) { return __builtin_amdgcn_rsqf(x); }
; template <int MODE> __device__ __forceinline__ void rwkv_item(const Params& P, int e, int c, int h, LAS float* slab, int lane) {
;     ...
;         for (int s = 0; s < SB; ++s) {
;             const float r = r1[s + 1] + (r1[s] - r1[s + 1]) * mu_r, k = k1[s + 1] + (k1[s] - k1[s + 1]) * mu_k, a = aa[s];
;             float kk = k * kkw;
;             const float ss = wave_sum(kk * kk);
;             kk *= frsq(fmaxf(ss, 1e-24f));
;             const float b = kk * a, kp = k * (1.f + (a - 1.f) * ka);
;             LAS float* st = slab + s * 512;
;             st[lane] = dd[s]; st[64 + lane] = kk; st[128 + lane] = b; st[192 + lane] = kp; st[256 + lane] = r; st[320 + lane] = vv[s];
;             if (MODE == 1) { st[384 + lane] = wave_sum(r * kp * rk); st[448 + lane] = gg[s]; }
;         }
	ds_read_b128 v[184:187], v209
	ds_read_b128 v[188:191], v209 offset:16
	ds_read_b128 v[200:203], v209 offset:32
	ds_read_b128 v[204:207], v209 offset:48
	s_waitcnt lgkmcnt(0)
	v_max_f32_e32 v127, 0x179abe15, v184
	v_rsq_f32_e32 v127, v127
	v_lshlrev_b32_e32 v81, 16, v81
	v_mul_f32_e32 v144, v144, v127
	v_mul_f32_e32 v124, v97, v144
	v_mul_f32_e32 v144, v144, v107
	v_mul_f32_e32 v107, v107, v89
	v_rcp_f32_e32 v127, v107
	v_mul_f32_e32 v176, v176, v107
	v_lshlrev_b32_e32 v167, 16, v167
	v_mul_f32_e32 v124, v124, v127
	v_mul_f32_e32 v136, v136, v127
	ds_write2st64_b32 v109, v144, v124 offset0:1 offset1:2
	ds_write2st64_b32 v109, v136, v176 offset0:3 offset1:4
	ds_write2st64_b32 v109, v81, v200 offset0:5 offset1:6
	ds_write_b32 v109, v167 offset:1792
	v_max_f32_e32 v127, 0x179abe15, v185
	v_rsq_f32_e32 v127, v127
	v_lshlrev_b32_e32 v82, 16, v82
	v_mul_f32_e32 v145, v145, v127
	v_mul_f32_e32 v124, v98, v145
	v_mul_f32_e32 v145, v145, v107
	v_mul_f32_e32 v107, v107, v90
	v_rcp_f32_e32 v127, v107
	v_mul_f32_e32 v177, v177, v107
	v_lshlrev_b32_e32 v168, 16, v168
	v_mul_f32_e32 v124, v124, v127
	v_mul_f32_e32 v137, v137, v127
	ds_write2st64_b32 v109, v145, v124 offset0:9 offset1:10
	ds_write2st64_b32 v109, v137, v177 offset0:11 offset1:12
	ds_write2st64_b32 v109, v82, v201 offset0:13 offset1:14
	ds_write_b32 v109, v168 offset:3840
	v_max_f32_e32 v127, 0x179abe15, v186
	v_rsq_f32_e32 v127, v127
	v_lshlrev_b32_e32 v83, 16, v83
	v_mul_f32_e32 v146, v146, v127
	v_mul_f32_e32 v124, v99, v146
	v_mul_f32_e32 v146, v146, v107
	v_mul_f32_e32 v107, v107, v91
	v_rcp_f32_e32 v127, v107
	v_mul_f32_e32 v178, v178, v107
	v_lshlrev_b32_e32 v169, 16, v169
	v_mul_f32_e32 v124, v124, v127
	v_mul_f32_e32 v138, v138, v127
	ds_write2st64_b32 v109, v146, v124 offset0:17 offset1:18
	ds_write2st64_b32 v109, v138, v178 offset0:19 offset1:20
	ds_write2st64_b32 v109, v83, v202 offset0:21 offset1:22
	ds_write_b32 v109, v169 offset:5888
	v_max_f32_e32 v127, 0x179abe15, v187
	v_rsq_f32_e32 v127, v127
	v_lshlrev_b32_e32 v84, 16, v84
	v_mul_f32_e32 v147, v147, v127
	v_mul_f32_e32 v124, v100, v147
	v_mul_f32_e32 v147, v147, v107
	v_mul_f32_e32 v107, v107, v92
	v_rcp_f32_e32 v127, v107
	v_mul_f32_e32 v179, v179, v107
	v_lshlrev_b32_e32 v170, 16, v170
	v_mul_f32_e32 v124, v124, v127
	v_mul_f32_e32 v139, v139, v127
	ds_write2st64_b32 v109, v147, v124 offset0:25 offset1:26
	ds_write2st64_b32 v109, v139, v179 offset0:27 offset1:28
	ds_write2st64_b32 v109, v84, v203 offset0:29 offset1:30
	ds_write_b32 v109, v170 offset:7936
	v_max_f32_e32 v127, 0x179abe15, v188
	v_rsq_f32_e32 v127, v127
	v_lshlrev_b32_e32 v85, 16, v85
	v_mul_f32_e32 v148, v148, v127
	v_mul_f32_e32 v124, v101, v148
	v_mul_f32_e32 v148, v148, v107
	v_mul_f32_e32 v107, v107, v93
	v_rcp_f32_e32 v127, v107
	v_mul_f32_e32 v180, v180, v107
	v_lshlrev_b32_e32 v171, 16, v171
	v_mul_f32_e32 v124, v124, v127
	v_mul_f32_e32 v140, v140, v127
	ds_write2st64_b32 v109, v148, v124 offset0:33 offset1:34
	ds_write2st64_b32 v109, v140, v180 offset0:35 offset1:36
	ds_write2st64_b32 v109, v85, v204 offset0:37 offset1:38
	ds_write_b32 v109, v171 offset:9984
	v_max_f32_e32 v127, 0x179abe15, v189
	v_rsq_f32_e32 v127, v127
	v_lshlrev_b32_e32 v86, 16, v86
	v_mul_f32_e32 v149, v149, v127
	v_mul_f32_e32 v124, v102, v149
	v_mul_f32_e32 v149, v149, v107
	v_mul_f32_e32 v107, v107, v94
	v_rcp_f32_e32 v127, v107
	v_mul_f32_e32 v181, v181, v107
	v_lshlrev_b32_e32 v172, 16, v172
	v_mul_f32_e32 v124, v124, v127
	v_mul_f32_e32 v141, v141, v127
	ds_write2st64_b32 v109, v149, v124 offset0:41 offset1:42
	ds_write2st64_b32 v109, v141, v181 offset0:43 offset1:44
	ds_write2st64_b32 v109, v86, v205 offset0:45 offset1:46
	ds_write_b32 v109, v172 offset:12032
	v_max_f32_e32 v127, 0x179abe15, v190
	v_rsq_f32_e32 v127, v127
	v_lshlrev_b32_e32 v87, 16, v87
	v_mul_f32_e32 v150, v150, v127
	v_mul_f32_e32 v124, v103, v150
	v_mul_f32_e32 v150, v150, v107
	v_mul_f32_e32 v107, v107, v95
	v_rcp_f32_e32 v127, v107
	v_mul_f32_e32 v182, v182, v107
	v_lshlrev_b32_e32 v173, 16, v173
	v_mul_f32_e32 v124, v124, v127
	v_mul_f32_e32 v142, v142, v127
	ds_write2st64_b32 v109, v150, v124 offset0:49 offset1:50
	ds_write2st64_b32 v109, v142, v182 offset0:51 offset1:52
	ds_write2st64_b32 v109, v87, v206 offset0:53 offset1:54
	ds_write_b32 v109, v173 offset:14080
	v_max_f32_e32 v127, 0x179abe15, v191
	v_rsq_f32_e32 v127, v127
	v_lshlrev_b32_e32 v88, 16, v88
	v_mul_f32_e32 v151, v151, v127
	v_mul_f32_e32 v124, v104, v151
	v_mul_f32_e32 v151, v151, v107
	v_mul_f32_e32 v107, v107, v96
	v_rcp_f32_e32 v127, v107
	v_mul_f32_e32 v183, v183, v107
	v_lshlrev_b32_e32 v174, 16, v174
	v_mul_f32_e32 v124, v124, v127
	v_mul_f32_e32 v143, v143, v127
	ds_write2st64_b32 v109, v151, v124 offset0:57 offset1:58
	ds_write2st64_b32 v109, v143, v183 offset0:59 offset1:60
	ds_write2st64_b32 v109, v88, v207 offset0:61 offset1:62
	ds_write_b32 v109, v174 offset:16128
	s_cmp_eq_u32 s1, 7
	s_cbranch_scc1 .Lm1_noload
; template <int MODE> __device__ __forceinline__ void rwkv_item(const Params& P, int e, int c, int h, LAS float* slab, int lane) {
;     ...
;         if (MODE == 1 && sb + 1 < RLCH / SB) RW_LOAD(tb + SB);
	global_load_ushort v65, v108, s[52:53]
	global_load_ushort v73, v108, s[52:53] offset:1024
	v_add_u32_e32 v115, 0xe00, v108
	global_load_ushort v66, v115, s[52:53]
	global_load_ushort v74, v115, s[52:53] offset:1024
	v_add_u32_e32 v122, 0x1c00, v108
	global_load_ushort v67, v122, s[52:53]
	global_load_ushort v75, v122, s[52:53] offset:1024
	v_add_u32_e32 v123, 0x2a00, v108
	global_load_ushort v68, v123, s[52:53]
	global_load_ushort v76, v123, s[52:53] offset:1024
	v_add_u32_e32 v114, 0x3800, v108
	global_load_ushort v69, v114, s[52:53]
	global_load_ushort v77, v114, s[52:53] offset:1024
	v_add_u32_e32 v115, 0x4600, v108
	global_load_ushort v70, v115, s[52:53]
	global_load_ushort v78, v115, s[52:53] offset:1024
	v_add_u32_e32 v122, 0x5400, v108
	global_load_ushort v71, v122, s[52:53]
	global_load_ushort v79, v122, s[52:53] offset:1024
	v_add_u32_e32 v123, 0x6200, v108
	global_load_ushort v72, v123, s[52:53]
	global_load_ushort v80, v123, s[52:53] offset:1024
	v_add_u32_e32 v114, 0x1000, v110
	global_load_ushort v81, v110, s[66:67]
	global_load_ushort v82, v110, s[66:67] offset:1024
	global_load_ushort v83, v110, s[66:67] offset:2048
	global_load_ushort v84, v110, s[66:67] offset:3072
	global_load_ushort v85, v114, s[66:67]
	global_load_ushort v86, v114, s[66:67] offset:1024
	global_load_ushort v87, v114, s[66:67] offset:2048
	global_load_ushort v88, v114, s[66:67] offset:3072
	global_load_ushort v97, v110, s[4:5]
	global_load_ushort v98, v110, s[4:5] offset:1024
	global_load_ushort v99, v110, s[4:5] offset:2048
	global_load_ushort v100, v110, s[4:5] offset:3072
	global_load_ushort v101, v114, s[4:5]
	global_load_ushort v102, v114, s[4:5] offset:1024
	global_load_ushort v103, v114, s[4:5] offset:2048
	global_load_ushort v104, v114, s[4:5] offset:3072
	global_load_ushort v167, v110, s[50:51]
	global_load_ushort v168, v110, s[50:51] offset:1024
	global_load_ushort v169, v110, s[50:51] offset:2048
	global_load_ushort v170, v110, s[50:51] offset:3072
	global_load_ushort v171, v114, s[50:51]
	global_load_ushort v172, v114, s[50:51] offset:1024
	global_load_ushort v173, v114, s[50:51] offset:2048
	global_load_ushort v174, v114, s[50:51] offset:3072
	v_add_u32_e32 v115, 0x1000, v112
	v_add_u32_e32 v122, 0x2000, v112
	v_add_u32_e32 v123, 0x3000, v112
	global_load_dword v89, v112, s[46:47]
	global_load_dword v90, v112, s[46:47] offset:2048
	global_load_dword v91, v115, s[46:47]
	global_load_dword v92, v115, s[46:47] offset:2048
	global_load_dword v93, v122, s[46:47]
	global_load_dword v94, v122, s[46:47] offset:2048
	global_load_dword v95, v123, s[46:47]
	global_load_dword v96, v123, s[46:47] offset:2048
	v_add_u32_e32 v108, 0x7000, v108
	v_add_u32_e32 v110, 0x2000, v110
	v_add_u32_e32 v112, 0x4000, v112

; template <int MODE> __device__ __forceinline__ void rwkv_item(const Params& P, int e, int c, int h, LAS float* slab, int lane) {
;     ...
;             if (NB == 2) RW_LD_DOT(0, 0);
;             const float v = st[320 + lane];
; #pragma unroll
;             for (int hb = 0; hb < NDB; ++hb) {
;                 if (NB == 2) { if (hb + 1 < NDB) RW_LD_DOT((hb + 1) & 1, hb + 1); else RW_LD_UPD(0, 0); } else RW_LD_DOT(0, hb);
;                 __builtin_amdgcn_sched_barrier(0);
; #pragma unroll
;                 for (int q = 0; q < DB; ++q) {
;                     const int qq = DB * hb + q; const f32x4 k4 = kd[hb & (NB - 1)][q];
;                     aS0 += S2[2 * qq] * (f32x2){k4.x, k4.y}; aS1 += S2[2 * qq + 1] * (f32x2){k4.z, k4.w};
;                     if (MODE == 0) { aC0 += C2[2 * qq] * (f32x2){k4.x, k4.y}; aC1 += C2[2 * qq + 1] * (f32x2){k4.z, k4.w}; }
;                 }
;                 __builtin_amdgcn_sched_barrier(0);
;             }
;             const float nsk = -((aS0.x + aS0.y) + (aS1.x + aS1.y));
;             const float nskC = -((aC0.x + aC0.y) + (aC1.x + aC1.y));
;             f32x2 y0 = {0.f, 0.f}, y1 = {0.f, 0.f};
; #pragma unroll
;             for (int qb = 0; qb < NUB; ++qb) {
;                 if (NB == 2) { if (qb + 1 < NUB) RW_LD_UPD((qb + 1) & 1, qb + 1); } else RW_LD_UPD(0, qb);
;                 __builtin_amdgcn_sched_barrier(0);
; #pragma unroll
;                 for (int q = 0; q < UB; ++q) {
;                     const int qq = UB * qb + q;
;                     const f32x4 w4 = wq[qb & (NB - 1)][q], b4 = bq[qb & (NB - 1)][q], k4 = kq[qb & (NB - 1)][q];
;                     if (MODE == 0) {
;                         S2[2 * qq] = S2[2 * qq] * (f32x2){w4.x, w4.y} + (f32x2){b4.x, b4.y} * nsk;
;                         S2[2 * qq + 1] = S2[2 * qq + 1] * (f32x2){w4.z, w4.w} + (f32x2){b4.z, b4.w} * nsk;
;                         C2[2 * qq] = C2[2 * qq] * (f32x2){w4.x, w4.y} + (f32x2){b4.x, b4.y} * nskC + (f32x2){k4.x, k4.y} * v;
;                         C2[2 * qq + 1] = C2[2 * qq + 1] * (f32x2){w4.z, w4.w} + (f32x2){b4.z, b4.w} * nskC + (f32x2){k4.z, k4.w} * v;
;                     } else {
;                         S2[2 * qq] = S2[2 * qq] * (f32x2){w4.x, w4.y} + (f32x2){b4.x, b4.y} * nsk + (f32x2){k4.x, k4.y} * v;
.Lm1_step:
	s_add_i32 s8, s3, s11
	v_add_u32_e32 v197, s11, v109
	v_mov_b32_e32 v196, s8
	ds_read_b32 v194, v197 offset:1280
	ds_read_b128 v[136:139], v196 offset:256
	ds_read_b128 v[140:143], v196 offset:272
	ds_read_b128 v[144:147], v196 offset:288
	ds_read_b128 v[148:151], v196 offset:304
	ds_read_b128 v[176:179], v196 offset:320
	ds_read_b128 v[180:183], v196 offset:336
	ds_read_b128 v[184:187], v196 offset:352
	ds_read_b128 v[188:191], v196 offset:368
	s_waitcnt lgkmcnt(7)
	v_pk_fma_f32 v[158:159], v[0:1], v[136:137], 0 op_sel_hi:[1,1,0]
	v_pk_fma_f32 v[160:161], v[2:3], v[138:139], 0 op_sel_hi:[1,1,0]
	ds_read_b128 v[136:139], v196 offset:384
	s_waitcnt lgkmcnt(7)
	v_pk_fma_f32 v[158:159], v[4:5], v[140:141], v[158:159]
	v_pk_fma_f32 v[160:161], v[6:7], v[142:143], v[160:161]
	ds_read_b128 v[140:143], v196 offset:400
	s_waitcnt lgkmcnt(7)
	v_pk_fma_f32 v[158:159], v[8:9], v[144:145], v[158:159]
	v_pk_fma_f32 v[160:161], v[10:11], v[146:147], v[160:161]
	ds_read_b128 v[144:147], v196 offset:416
	s_waitcnt lgkmcnt(7)
	v_pk_fma_f32 v[158:159], v[12:13], v[148:149], v[158:159]
	v_pk_fma_f32 v[160:161], v[14:15], v[150:151], v[160:161]
	ds_read_b128 v[148:151], v196 offset:432
	s_waitcnt lgkmcnt(7)
	v_pk_fma_f32 v[158:159], v[16:17], v[176:177], v[158:159]
	v_pk_fma_f32 v[160:161], v[18:19], v[178:179], v[160:161]
	ds_read_b128 v[176:179], v196 offset:448
	s_waitcnt lgkmcnt(7)
	v_pk_fma_f32 v[158:159], v[20:21], v[180:181], v[158:159]
	v_pk_fma_f32 v[160:161], v[22:23], v[182:183], v[160:161]
	ds_read_b128 v[180:183], v196 offset:464
	s_waitcnt lgkmcnt(7)
	v_pk_fma_f32 v[158:159], v[24:25], v[184:185], v[158:159]
	v_pk_fma_f32 v[160:161], v[26:27], v[186:187], v[160:161]
	ds_read_b128 v[184:187], v196 offset:480
	s_waitcnt lgkmcnt(7)
	v_pk_fma_f32 v[158:159], v[28:29], v[188:189], v[158:159]
	v_pk_fma_f32 v[160:161], v[30:31], v[190:191], v[160:161]
	ds_read_b128 v[188:191], v196 offset:496
	s_waitcnt lgkmcnt(7)
	v_pk_fma_f32 v[158:159], v[32:33], v[136:137], v[158:159]
	v_pk_fma_f32 v[160:161], v[34:35], v[138:139], v[160:161]
	ds_read_b128 v[136:139], v196 offset:512
	s_waitcnt lgkmcnt(7)
	v_pk_fma_f32 v[158:159], v[36:37], v[140:141], v[158:159]
	v_pk_fma_f32 v[160:161], v[38:39], v[142:143], v[160:161]
	ds_read_b128 v[140:143], v196 offset:768
	s_waitcnt lgkmcnt(7)
	v_pk_fma_f32 v[158:159], v[40:41], v[144:145], v[158:159]
	v_pk_fma_f32 v[160:161], v[42:43], v[146:147], v[160:161]
	ds_read_b128 v[144:147], v196 offset:1024
	s_waitcnt lgkmcnt(7)
	v_pk_fma_f32 v[158:159], v[44:45], v[148:149], v[158:159]
	v_pk_fma_f32 v[160:161], v[46:47], v[150:151], v[160:161]
	ds_read_b128 v[148:151], v196 offset:528
	s_waitcnt lgkmcnt(7)
	v_pk_fma_f32 v[158:159], v[48:49], v[176:177], v[158:159]
	v_pk_fma_f32 v[160:161], v[50:51], v[178:179], v[160:161]
	ds_read_b128 v[176:179], v196 offset:784
	s_waitcnt lgkmcnt(7)
	v_pk_fma_f32 v[158:159], v[52:53], v[180:181], v[158:159]
	v_pk_fma_f32 v[160:161], v[54:55], v[182:183], v[160:161]
	ds_read_b128 v[180:183], v196 offset:1040
	s_waitcnt lgkmcnt(7)
	v_pk_fma_f32 v[158:159], v[56:57], v[184:185], v[158:159]
	v_pk_fma_f32 v[160:161], v[58:59], v[186:187], v[160:161]
	ds_read_b128 v[184:187], v196 offset:544
	s_waitcnt lgkmcnt(7)
	v_pk_fma_f32 v[158:159], v[60:61], v[188:189], v[158:159]
	v_pk_fma_f32 v[160:161], v[62:63], v[190:191], v[160:161]
	ds_read_b128 v[188:191], v196 offset:800
	v_add_f32_e32 v192, v158, v159
	v_add_f32_e32 v198, v160, v161
	v_add_f32_e32 v192, v198, v192
	s_waitcnt lgkmcnt(7)
	v_pk_fma_f32 v[0:1], v[136:137], v[192:193], v[0:1] op_sel_hi:[1,0,1] neg_lo:[0,1,0] neg_hi:[0,1,0]
	v_pk_fma_f32 v[2:3], v[138:139], v[192:193], v[2:3] op_sel_hi:[1,0,1] neg_lo:[0,1,0] neg_hi:[0,1,0]
	ds_read_b128 v[136:139], v196 offset:1056
	s_waitcnt lgkmcnt(7)
	v_pk_fma_f32 v[0:1], v[194:195], v[140:141], v[0:1] op_sel_hi:[0,1,1]
	v_pk_fma_f32 v[2:3], v[194:195], v[142:143], v[2:3] op_sel_hi:[0,1,1]
	ds_read_b128 v[140:143], v196 offset:560
	s_waitcnt lgkmcnt(7)
	v_pk_fma_f32 v[162:163], v[144:145], v[0:1], 0 op_sel_hi:[1,1,0]
	v_pk_fma_f32 v[164:165], v[146:147], v[2:3], 0 op_sel_hi:[1,1,0]
	ds_read_b128 v[144:147], v196 offset:816
	s_waitcnt lgkmcnt(7)
	v_pk_fma_f32 v[4:5], v[148:149], v[192:193], v[4:5] op_sel_hi:[1,0,1] neg_lo:[0,1,0] neg_hi:[0,1,0]
	v_pk_fma_f32 v[6:7], v[150:151], v[192:193], v[6:7] op_sel_hi:[1,0,1] neg_lo:[0,1,0] neg_hi:[0,1,0]
	ds_read_b128 v[148:151], v196 offset:1072
	s_waitcnt lgkmcnt(7)
	v_pk_fma_f32 v[4:5], v[194:195], v[176:177], v[4:5] op_sel_hi:[0,1,1]
	v_pk_fma_f32 v[6:7], v[194:195], v[178:179], v[6:7] op_sel_hi:[0,1,1]
	ds_read_b128 v[176:179], v196 offset:576
	s_waitcnt lgkmcnt(7)
	v_pk_fma_f32 v[162:163], v[180:181], v[4:5], v[162:163]
	v_pk_fma_f32 v[164:165], v[182:183], v[6:7], v[164:165]
	ds_read_b128 v[180:183], v196 offset:832
	s_waitcnt lgkmcnt(7)
	v_pk_fma_f32 v[8:9], v[184:185], v[192:193], v[8:9] op_sel_hi:[1,0,1] neg_lo:[0,1,0] neg_hi:[0,1,0]
	v_pk_fma_f32 v[10:11], v[186:187], v[192:193], v[10:11] op_sel_hi:[1,0,1] neg_lo:[0,1,0] neg_hi:[0,1,0]
	ds_read_b128 v[184:187], v196 offset:1088
	s_waitcnt lgkmcnt(7)
	v_pk_fma_f32 v[8:9], v[194:195], v[188:189], v[8:9] op_sel_hi:[0,1,1]
	v_pk_fma_f32 v[10:11], v[194:195], v[190:191], v[10:11] op_sel_hi:[0,1,1]
	ds_read_b128 v[188:191], v196 offset:592
	s_waitcnt lgkmcnt(7)
	v_pk_fma_f32 v[162:163], v[136:137], v[8:9], v[162:163]
	v_pk_fma_f32 v[164:165], v[138:139], v[10:11], v[164:165]
	ds_read_b128 v[136:139], v196 offset:848
	s_waitcnt lgkmcnt(7)
	v_pk_fma_f32 v[12:13], v[140:141], v[192:193], v[12:13] op_sel_hi:[1,0,1] neg_lo:[0,1,0] neg_hi:[0,1,0]
	v_pk_fma_f32 v[14:15], v[142:143], v[192:193], v[14:15] op_sel_hi:[1,0,1] neg_lo:[0,1,0] neg_hi:[0,1,0]
	ds_read_b128 v[140:143], v196 offset:1104
	s_waitcnt lgkmcnt(7)
; #define RW_LD_UPD(buf, qb) do { _Pragma("unroll") for (int q_ = 0; q_ < UB; ++q_) { const int qq_ = UB * (qb) + q_; \
;                 wq[buf][q_] = *(const LAS f32x4*)(st + 4 * qq_); bq[buf][q_] = *(const LAS f32x4*)(st + 128 + 4 * qq_); kq[buf][q_] = *(const LAS f32x4*)(st + 192 + 4 * qq_); \
;                 if (MODE == 1) rq[buf][q_] = *(const LAS f32x4*)(st + 256 + 4 * qq_); } } while (0)
; template <int MODE> __device__ __forceinline__ void rwkv_item(const Params& P, int e, int c, int h, LAS float* slab, int lane) {
;     ...
;             for (int qb = 0; qb < NUB; ++qb) {
;                 if (NB == 2) { if (qb + 1 < NUB) RW_LD_UPD((qb + 1) & 1, qb + 1); } else RW_LD_UPD(0, qb);
;                 __builtin_amdgcn_sched_barrier(0);
; #pragma unroll
;                 for (int q = 0; q < UB; ++q) {
;                     const int qq = UB * qb + q;
;                     const f32x4 w4 = wq[qb & (NB - 1)][q], b4 = bq[qb & (NB - 1)][q], k4 = kq[qb & (NB - 1)][q];
;                     if (MODE == 0) {
;                         S2[2 * qq] = S2[2 * qq] * (f32x2){w4.x, w4.y} + (f32x2){b4.x, b4.y} * nsk;
;                         S2[2 * qq + 1] = S2[2 * qq + 1] * (f32x2){w4.z, w4.w} + (f32x2){b4.z, b4.w} * nsk;
;                         C2[2 * qq] = C2[2 * qq] * (f32x2){w4.x, w4.y} + (f32x2){b4.x, b4.y} * nskC + (f32x2){k4.x, k4.y} * v;
;                         C2[2 * qq + 1] = C2[2 * qq + 1] * (f32x2){w4.z, w4.w} + (f32x2){b4.z, b4.w} * nskC + (f32x2){k4.z, k4.w} * v;
;                     } else {
;                         S2[2 * qq] = S2[2 * qq] * (f32x2){w4.x, w4.y} + (f32x2){b4.x, b4.y} * nsk + (f32x2){k4.x, k4.y} * v;
;                         S2[2 * qq + 1] = S2[2 * qq + 1] * (f32x2){w4.z, w4.w} + (f32x2){b4.z, b4.w} * nsk + (f32x2){k4.z, k4.w} * v;
;                         const f32x4 r4 = rq[qb & (NB - 1)][q]; y0 += S2[2 * qq] * (f32x2){r4.x, r4.y}; y1 += S2[2 * qq + 1] * (f32x2){r4.z, r4.w};
;                     }
	v_pk_fma_f32 v[12:13], v[194:195], v[144:145], v[12:13] op_sel_hi:[0,1,1]
	v_pk_fma_f32 v[14:15], v[194:195], v[146:147], v[14:15] op_sel_hi:[0,1,1]
	ds_read_b128 v[144:147], v196 offset:608
	s_waitcnt lgkmcnt(7)
	v_pk_fma_f32 v[162:163], v[148:149], v[12:13], v[162:163]
	v_pk_fma_f32 v[164:165], v[150:151], v[14:15], v[164:165]
	ds_read_b128 v[148:151], v196 offset:864
	s_waitcnt lgkmcnt(7)
	v_pk_fma_f32 v[16:17], v[176:177], v[192:193], v[16:17] op_sel_hi:[1,0,1] neg_lo:[0,1,0] neg_hi:[0,1,0]
	v_pk_fma_f32 v[18:19], v[178:179], v[192:193], v[18:19] op_sel_hi:[1,0,1] neg_lo:[0,1,0] neg_hi:[0,1,0]
	ds_read_b128 v[176:179], v196 offset:1120
	s_waitcnt lgkmcnt(7)
	v_pk_fma_f32 v[16:17], v[194:195], v[180:181], v[16:17] op_sel_hi:[0,1,1]
	v_pk_fma_f32 v[18:19], v[194:195], v[182:183], v[18:19] op_sel_hi:[0,1,1]
	ds_read_b128 v[180:183], v196 offset:624
	s_waitcnt lgkmcnt(7)
	v_pk_fma_f32 v[162:163], v[184:185], v[16:17], v[162:163]
	v_pk_fma_f32 v[164:165], v[186:187], v[18:19], v[164:165]
	ds_read_b128 v[184:187], v196 offset:880
	s_waitcnt lgkmcnt(7)
	v_pk_fma_f32 v[20:21], v[188:189], v[192:193], v[20:21] op_sel_hi:[1,0,1] neg_lo:[0,1,0] neg_hi:[0,1,0]
	v_pk_fma_f32 v[22:23], v[190:191], v[192:193], v[22:23] op_sel_hi:[1,0,1] neg_lo:[0,1,0] neg_hi:[0,1,0]
	ds_read_b128 v[188:191], v196 offset:1136
	s_waitcnt lgkmcnt(7)
	v_pk_fma_f32 v[20:21], v[194:195], v[136:137], v[20:21] op_sel_hi:[0,1,1]
	v_pk_fma_f32 v[22:23], v[194:195], v[138:139], v[22:23] op_sel_hi:[0,1,1]
	ds_read_b128 v[136:139], v196 offset:640
	s_waitcnt lgkmcnt(7)
	v_pk_fma_f32 v[162:163], v[140:141], v[20:21], v[162:163]
	v_pk_fma_f32 v[164:165], v[142:143], v[22:23], v[164:165]
	ds_read_b128 v[140:143], v196 offset:896
	s_waitcnt lgkmcnt(7)
	v_pk_fma_f32 v[24:25], v[144:145], v[192:193], v[24:25] op_sel_hi:[1,0,1] neg_lo:[0,1,0] neg_hi:[0,1,0]
	v_pk_fma_f32 v[26:27], v[146:147], v[192:193], v[26:27] op_sel_hi:[1,0,1] neg_lo:[0,1,0] neg_hi:[0,1,0]
	ds_read_b128 v[144:147], v196 offset:1152
	s_waitcnt lgkmcnt(7)
	v_pk_fma_f32 v[24:25], v[194:195], v[148:149], v[24:25] op_sel_hi:[0,1,1]
	v_pk_fma_f32 v[26:27], v[194:195], v[150:151], v[26:27] op_sel_hi:[0,1,1]
	ds_read_b128 v[148:151], v196 offset:656
	s_waitcnt lgkmcnt(7)
	v_pk_fma_f32 v[162:163], v[176:177], v[24:25], v[162:163]
	v_pk_fma_f32 v[164:165], v[178:179], v[26:27], v[164:165]
	ds_read_b128 v[176:179], v196 offset:912
	s_waitcnt lgkmcnt(7)
	v_pk_fma_f32 v[28:29], v[180:181], v[192:193], v[28:29] op_sel_hi:[1,0,1] neg_lo:[0,1,0] neg_hi:[0,1,0]
	v_pk_fma_f32 v[30:31], v[182:183], v[192:193], v[30:31] op_sel_hi:[1,0,1] neg_lo:[0,1,0] neg_hi:[0,1,0]
	ds_read_b128 v[180:183], v196 offset:1168
	s_waitcnt lgkmcnt(7)
	v_pk_fma_f32 v[28:29], v[194:195], v[184:185], v[28:29] op_sel_hi:[0,1,1]
	v_pk_fma_f32 v[30:31], v[194:195], v[186:187], v[30:31] op_sel_hi:[0,1,1]
	ds_read_b128 v[184:187], v196 offset:672
	s_waitcnt lgkmcnt(7)
	v_pk_fma_f32 v[162:163], v[188:189], v[28:29], v[162:163]
	v_pk_fma_f32 v[164:165], v[190:191], v[30:31], v[164:165]
	ds_read_b128 v[188:191], v196 offset:928
	s_waitcnt lgkmcnt(7)
	v_pk_fma_f32 v[32:33], v[136:137], v[192:193], v[32:33] op_sel_hi:[1,0,1] neg_lo:[0,1,0] neg_hi:[0,1,0]
	v_pk_fma_f32 v[34:35], v[138:139], v[192:193], v[34:35] op_sel_hi:[1,0,1] neg_lo:[0,1,0] neg_hi:[0,1,0]
	ds_read_b128 v[136:139], v196 offset:1184
	s_waitcnt lgkmcnt(7)
	v_pk_fma_f32 v[32:33], v[194:195], v[140:141], v[32:33] op_sel_hi:[0,1,1]
	v_pk_fma_f32 v[34:35], v[194:195], v[142:143], v[34:35] op_sel_hi:[0,1,1]
	ds_read_b128 v[140:143], v196 offset:688
	s_waitcnt lgkmcnt(7)
	v_pk_fma_f32 v[162:163], v[144:145], v[32:33], v[162:163]
	v_pk_fma_f32 v[164:165], v[146:147], v[34:35], v[164:165]
	ds_read_b128 v[144:147], v196 offset:944
	s_waitcnt lgkmcnt(7)
	v_pk_fma_f32 v[36:37], v[148:149], v[192:193], v[36:37] op_sel_hi:[1,0,1] neg_lo:[0,1,0] neg_hi:[0,1,0]
	v_pk_fma_f32 v[38:39], v[150:151], v[192:193], v[38:39] op_sel_hi:[1,0,1] neg_lo:[0,1,0] neg_hi:[0,1,0]
	ds_read_b128 v[148:151], v196 offset:1200
	s_waitcnt lgkmcnt(7)
	v_pk_fma_f32 v[36:37], v[194:195], v[176:177], v[36:37] op_sel_hi:[0,1,1]
	v_pk_fma_f32 v[38:39], v[194:195], v[178:179], v[38:39] op_sel_hi:[0,1,1]
	ds_read_b128 v[176:179], v196 offset:704
	s_waitcnt lgkmcnt(7)
	v_pk_fma_f32 v[162:163], v[180:181], v[36:37], v[162:163]
	v_pk_fma_f32 v[164:165], v[182:183], v[38:39], v[164:165]
	ds_read_b128 v[180:183], v196 offset:960
	s_waitcnt lgkmcnt(7)
	v_pk_fma_f32 v[40:41], v[184:185], v[192:193], v[40:41] op_sel_hi:[1,0,1] neg_lo:[0,1,0] neg_hi:[0,1,0]
	v_pk_fma_f32 v[42:43], v[186:187], v[192:193], v[42:43] op_sel_hi:[1,0,1] neg_lo:[0,1,0] neg_hi:[0,1,0]
	ds_read_b128 v[184:187], v196 offset:1216
	s_waitcnt lgkmcnt(7)
	v_pk_fma_f32 v[40:41], v[194:195], v[188:189], v[40:41] op_sel_hi:[0,1,1]
	v_pk_fma_f32 v[42:43], v[194:195], v[190:191], v[42:43] op_sel_hi:[0,1,1]
	ds_read_b128 v[188:191], v196 offset:720
	s_waitcnt lgkmcnt(7)
	v_pk_fma_f32 v[162:163], v[136:137], v[40:41], v[162:163]
	v_pk_fma_f32 v[164:165], v[138:139], v[42:43], v[164:165]
	ds_read_b128 v[136:139], v196 offset:976
	s_waitcnt lgkmcnt(7)
	v_pk_fma_f32 v[44:45], v[140:141], v[192:193], v[44:45] op_sel_hi:[1,0,1] neg_lo:[0,1,0] neg_hi:[0,1,0]
	v_pk_fma_f32 v[46:47], v[142:143], v[192:193], v[46:47] op_sel_hi:[1,0,1] neg_lo:[0,1,0] neg_hi:[0,1,0]
	ds_read_b128 v[140:143], v196 offset:1232
	s_waitcnt lgkmcnt(7)
	v_pk_fma_f32 v[44:45], v[194:195], v[144:145], v[44:45] op_sel_hi:[0,1,1]
	v_pk_fma_f32 v[46:47], v[194:195], v[146:147], v[46:47] op_sel_hi:[0,1,1]
	ds_read_b128 v[144:147], v196 offset:736
	s_waitcnt lgkmcnt(7)
; #define LAS __attribute__((address_space(3)))
; #define RW_LD_UPD(buf, qb) do { _Pragma("unroll") for (int q_ = 0; q_ < UB; ++q_) { const int qq_ = UB * (qb) + q_; \
;                 wq[buf][q_] = *(const LAS f32x4*)(st + 4 * qq_); bq[buf][q_] = *(const LAS f32x4*)(st + 128 + 4 * qq_); kq[buf][q_] = *(const LAS f32x4*)(st + 192 + 4 * qq_); \
;                 if (MODE == 1) rq[buf][q_] = *(const LAS f32x4*)(st + 256 + 4 * qq_); } } while (0)
; template <int MODE> __device__ __forceinline__ void rwkv_item(const Params& P, int e, int c, int h, LAS float* slab, int lane) {
;     ...
;             for (int qb = 0; qb < NUB; ++qb) {
;                 if (NB == 2) { if (qb + 1 < NUB) RW_LD_UPD((qb + 1) & 1, qb + 1); } else RW_LD_UPD(0, qb);
;                 __builtin_amdgcn_sched_barrier(0);
; #pragma unroll
;                 for (int q = 0; q < UB; ++q) {
;                     const int qq = UB * qb + q;
;                     const f32x4 w4 = wq[qb & (NB - 1)][q], b4 = bq[qb & (NB - 1)][q], k4 = kq[qb & (NB - 1)][q];
;                     if (MODE == 0) {
;                         S2[2 * qq] = S2[2 * qq] * (f32x2){w4.x, w4.y} + (f32x2){b4.x, b4.y} * nsk;
;                         S2[2 * qq + 1] = S2[2 * qq + 1] * (f32x2){w4.z, w4.w} + (f32x2){b4.z, b4.w} * nsk;
;                         C2[2 * qq] = C2[2 * qq] * (f32x2){w4.x, w4.y} + (f32x2){b4.x, b4.y} * nskC + (f32x2){k4.x, k4.y} * v;
;                         C2[2 * qq + 1] = C2[2 * qq + 1] * (f32x2){w4.z, w4.w} + (f32x2){b4.z, b4.w} * nskC + (f32x2){k4.z, k4.w} * v;
;                     } else {
;                         S2[2 * qq] = S2[2 * qq] * (f32x2){w4.x, w4.y} + (f32x2){b4.x, b4.y} * nsk + (f32x2){k4.x, k4.y} * v;
;                         S2[2 * qq + 1] = S2[2 * qq + 1] * (f32x2){w4.z, w4.w} + (f32x2){b4.z, b4.w} * nsk + (f32x2){k4.z, k4.w} * v;
;                         const f32x4 r4 = rq[qb & (NB - 1)][q]; y0 += S2[2 * qq] * (f32x2){r4.x, r4.y}; y1 += S2[2 * qq + 1] * (f32x2){r4.z, r4.w};
;                     }
;                 }
;                 __builtin_amdgcn_sched_barrier(0);
;             }
;     ...
;             if (MODE == 1) ((LAS float*)st)[lane] = (y0.x + y0.y) + (y1.x + y1.y);
	v_pk_fma_f32 v[162:163], v[148:149], v[44:45], v[162:163]
	v_pk_fma_f32 v[164:165], v[150:151], v[46:47], v[164:165]
	ds_read_b128 v[148:151], v196 offset:992
	s_waitcnt lgkmcnt(7)
	v_pk_fma_f32 v[48:49], v[176:177], v[192:193], v[48:49] op_sel_hi:[1,0,1] neg_lo:[0,1,0] neg_hi:[0,1,0]
	v_pk_fma_f32 v[50:51], v[178:179], v[192:193], v[50:51] op_sel_hi:[1,0,1] neg_lo:[0,1,0] neg_hi:[0,1,0]
	ds_read_b128 v[176:179], v196 offset:1248
	s_waitcnt lgkmcnt(7)
	v_pk_fma_f32 v[48:49], v[194:195], v[180:181], v[48:49] op_sel_hi:[0,1,1]
	v_pk_fma_f32 v[50:51], v[194:195], v[182:183], v[50:51] op_sel_hi:[0,1,1]
	ds_read_b128 v[180:183], v196 offset:752
	s_waitcnt lgkmcnt(7)
	v_pk_fma_f32 v[162:163], v[184:185], v[48:49], v[162:163]
	v_pk_fma_f32 v[164:165], v[186:187], v[50:51], v[164:165]
	ds_read_b128 v[184:187], v196 offset:1008
	s_waitcnt lgkmcnt(7)
	v_pk_fma_f32 v[52:53], v[188:189], v[192:193], v[52:53] op_sel_hi:[1,0,1] neg_lo:[0,1,0] neg_hi:[0,1,0]
	v_pk_fma_f32 v[54:55], v[190:191], v[192:193], v[54:55] op_sel_hi:[1,0,1] neg_lo:[0,1,0] neg_hi:[0,1,0]
	ds_read_b128 v[188:191], v196 offset:1264
	s_waitcnt lgkmcnt(7)
	v_pk_fma_f32 v[52:53], v[194:195], v[136:137], v[52:53] op_sel_hi:[0,1,1]
	v_pk_fma_f32 v[54:55], v[194:195], v[138:139], v[54:55] op_sel_hi:[0,1,1]
	s_waitcnt lgkmcnt(6)
	v_pk_fma_f32 v[162:163], v[140:141], v[52:53], v[162:163]
	v_pk_fma_f32 v[164:165], v[142:143], v[54:55], v[164:165]
	s_waitcnt lgkmcnt(5)
	v_pk_fma_f32 v[56:57], v[144:145], v[192:193], v[56:57] op_sel_hi:[1,0,1] neg_lo:[0,1,0] neg_hi:[0,1,0]
	v_pk_fma_f32 v[58:59], v[146:147], v[192:193], v[58:59] op_sel_hi:[1,0,1] neg_lo:[0,1,0] neg_hi:[0,1,0]
	s_waitcnt lgkmcnt(4)
	v_pk_fma_f32 v[56:57], v[194:195], v[148:149], v[56:57] op_sel_hi:[0,1,1]
	v_pk_fma_f32 v[58:59], v[194:195], v[150:151], v[58:59] op_sel_hi:[0,1,1]
	s_waitcnt lgkmcnt(3)
	v_pk_fma_f32 v[162:163], v[176:177], v[56:57], v[162:163]
	v_pk_fma_f32 v[164:165], v[178:179], v[58:59], v[164:165]
	s_waitcnt lgkmcnt(2)
	v_pk_fma_f32 v[60:61], v[180:181], v[192:193], v[60:61] op_sel_hi:[1,0,1] neg_lo:[0,1,0] neg_hi:[0,1,0]
	v_pk_fma_f32 v[62:63], v[182:183], v[192:193], v[62:63] op_sel_hi:[1,0,1] neg_lo:[0,1,0] neg_hi:[0,1,0]
	s_waitcnt lgkmcnt(1)
	v_pk_fma_f32 v[60:61], v[194:195], v[184:185], v[60:61] op_sel_hi:[0,1,1]
	v_pk_fma_f32 v[62:63], v[194:195], v[186:187], v[62:63] op_sel_hi:[0,1,1]
	s_waitcnt lgkmcnt(0)
	v_pk_fma_f32 v[162:163], v[188:189], v[60:61], v[162:163]
	v_pk_fma_f32 v[164:165], v[190:191], v[62:63], v[164:165]
	v_add_f32_e32 v198, v162, v163
	v_add_f32_e32 v192, v164, v165
	v_add_f32_e32 v198, v192, v198
	s_addk_i32 s11, 0x800
	ds_write_b32 v197, v198
	s_cmpk_eq_i32 s11, 0x4000
	s_cbranch_scc0 .Lm1_step
; #define LAS __attribute__((address_space(3)))
; __device__ __forceinline__ unsigned f2bf(float f) { unsigned u = __float_as_uint(f); return (u + 0x7fffu + ((u >> 16) & 1u)) >> 16; }
; __device__ __forceinline__ float frsq(float x) { return __builtin_amdgcn_rsqf(x); }
; #define LDS_WAIT() asm volatile("s_waitcnt lgkmcnt(0)" ::: "memory")
; template <int MODE> __device__ __forceinline__ void rwkv_item(const Params& P, int e, int c, int h, LAS float* slab, int lane) {
;     ...
;         if (MODE == 1) {
;             LDS_WAIT();
; #pragma unroll
;             for (int s = 0; s < SB; ++s) {
;                 const LAS float* st = slab + s * 512;
;                 const float y = st[lane], v = st[320 + lane];
;                 const float mean = wave_sum(y) * (1.f / 64.f), d = y - mean;
;                 const float var = wave_sum(d * d) * (1.f / 64.f);
;                 const float yn = d * frsq(var + 64e-5f) * lnw + lnb;
;                 MIX[(size_t)(tb + s) * D + ch] = (bf16)f2bf((yn + st[384 + lane] * v) * st[448 + lane]);
;             }
;         }
	s_waitcnt lgkmcnt(0)
	s_waitcnt vmcnt(48)
	ds_read_b128 v[192:195], v175
	ds_read_b128 v[196:199], v175 offset:16
	ds_read2st64_b32 v[136:137], v109 offset0:0 offset1:5
	ds_read2st64_b32 v[138:139], v109 offset0:8 offset1:13
	ds_read2st64_b32 v[140:141], v109 offset0:16 offset1:21
	ds_read2st64_b32 v[142:143], v109 offset0:24 offset1:29
	ds_read2st64_b32 v[144:145], v109 offset0:32 offset1:37
	ds_read2st64_b32 v[146:147], v109 offset0:40 offset1:45
	ds_read2st64_b32 v[148:149], v109 offset0:48 offset1:53
	ds_read2st64_b32 v[150:151], v109 offset0:56 offset1:61
	s_waitcnt lgkmcnt(8)
	v_add_f32_e32 v192, v192, v193
	v_add_f32_e32 v194, v194, v195
	v_add_f32_e32 v196, v196, v197
	v_add_f32_e32 v198, v198, v199
	v_add_f32_e32 v192, v192, v194
	v_add_f32_e32 v196, v196, v198
	v_add_f32_e32 v192, v192, v196
	s_nop 1
	v_add_f32_dpp v192, v192, v192 quad_perm:[1,0,3,2] row_mask:0xf bank_mask:0xf bound_ctrl:1
	s_nop 1
	v_add_f32_dpp v192, v192, v192 quad_perm:[2,3,0,1] row_mask:0xf bank_mask:0xf bound_ctrl:1
	s_nop 1
	v_add_f32_dpp v192, v192, v192 row_half_mirror row_mask:0xf bank_mask:0xf bound_ctrl:1
	ds_write_b32 v208, v192
	s_waitcnt lgkmcnt(0)
	ds_read_b128 v[184:187], v209
	ds_read_b128 v[188:191], v209 offset:16
	s_waitcnt lgkmcnt(0)
	v_fmamk_f32 v136, v184, 0xbc800000, v136
	v_mul_f32_e32 v124, v136, v136
	ds_write_b32 v109, v124
	v_fmamk_f32 v138, v185, 0xbc800000, v138
	v_mul_f32_e32 v124, v138, v138
	ds_write_b32 v109, v124 offset:2048
	v_fmamk_f32 v140, v186, 0xbc800000, v140
	v_mul_f32_e32 v124, v140, v140
	ds_write_b32 v109, v124 offset:4096
	v_fmamk_f32 v142, v187, 0xbc800000, v142
	v_mul_f32_e32 v124, v142, v142
	ds_write_b32 v109, v124 offset:6144
	v_fmamk_f32 v144, v188, 0xbc800000, v144
	v_mul_f32_e32 v124, v144, v144
	ds_write_b32 v109, v124 offset:8192
	v_fmamk_f32 v146, v189, 0xbc800000, v146
	v_mul_f32_e32 v124, v146, v146
	ds_write_b32 v109, v124 offset:10240
	v_fmamk_f32 v148, v190, 0xbc800000, v148
	v_mul_f32_e32 v124, v148, v148
	ds_write_b32 v109, v124 offset:12288
	v_fmamk_f32 v150, v191, 0xbc800000, v150
	v_mul_f32_e32 v124, v150, v150
	ds_write_b32 v109, v124 offset:14336
	s_waitcnt lgkmcnt(0)
	ds_read_b128 v[192:195], v175
	ds_read_b128 v[196:199], v175 offset:16
	s_waitcnt lgkmcnt(0)
	v_add_f32_e32 v192, v192, v193
	v_add_f32_e32 v194, v194, v195
	v_add_f32_e32 v196, v196, v197
	v_add_f32_e32 v198, v198, v199
	v_add_f32_e32 v192, v192, v194
	v_add_f32_e32 v196, v196, v198
	v_add_f32_e32 v192, v192, v196
	s_nop 1
	v_add_f32_dpp v192, v192, v192 quad_perm:[1,0,3,2] row_mask:0xf bank_mask:0xf bound_ctrl:1
	s_nop 1
	v_add_f32_dpp v192, v192, v192 quad_perm:[2,3,0,1] row_mask:0xf bank_mask:0xf bound_ctrl:1
	s_nop 1
	v_add_f32_dpp v192, v192, v192 row_half_mirror row_mask:0xf bank_mask:0xf bound_ctrl:1
	ds_write_b32 v208, v192
	s_waitcnt lgkmcnt(0)
	ds_read_b128 v[184:187], v209
	ds_read_b128 v[188:191], v209 offset:16
	ds_read2st64_b32 v[128:129], v109 offset0:6 offset1:7
	ds_read2st64_b32 v[130:131], v109 offset0:14 offset1:15
	ds_read2st64_b32 v[132:133], v109 offset0:22 offset1:23
	ds_read2st64_b32 v[134:135], v109 offset0:30 offset1:31
	ds_read2st64_b32 v[192:193], v109 offset0:38 offset1:39
	ds_read2st64_b32 v[194:195], v109 offset0:46 offset1:47
	ds_read2st64_b32 v[196:197], v109 offset0:54 offset1:55
	ds_read2st64_b32 v[198:199], v109 offset0:62 offset1:63
	s_waitcnt lgkmcnt(7)
	v_fmamk_f32 v124, v184, 0x3c800000, v221
	v_rsq_f32_e32 v124, v124
	v_add_u32_e32 v127, 0x0, v113
	v_mul_f32_e32 v136, v136, v124
	v_fma_f32 v136, v120, v136, v121
	v_fmac_f32_e32 v136, v137, v128
	v_mul_f32_e32 v136, v129, v136
	v_bfe_u32 v125, v136, 16, 1
	v_add3_u32 v126, v136, v125, s33
	global_store_short_d16_hi v127, v126, s[70:71]
	s_waitcnt lgkmcnt(6)
	v_fmamk_f32 v124, v185, 0x3c800000, v221
	v_rsq_f32_e32 v124, v124
	v_add_u32_e32 v127, 0x800, v113
	v_mul_f32_e32 v138, v138, v124
	v_fma_f32 v138, v120, v138, v121
	v_fmac_f32_e32 v138, v139, v130
	v_mul_f32_e32 v138, v131, v138
	v_bfe_u32 v125, v138, 16, 1
	v_add3_u32 v126, v138, v125, s33
	global_store_short_d16_hi v127, v126, s[70:71]
	s_waitcnt lgkmcnt(5)
	v_fmamk_f32 v124, v186, 0x3c800000, v221
	v_rsq_f32_e32 v124, v124
	v_add_u32_e32 v127, 0x1000, v113
	v_mul_f32_e32 v140, v140, v124
	v_fma_f32 v140, v120, v140, v121
	v_fmac_f32_e32 v140, v141, v132
	v_mul_f32_e32 v140, v133, v140
	v_bfe_u32 v125, v140, 16, 1
	v_add3_u32 v126, v140, v125, s33
	global_store_short_d16_hi v127, v126, s[70:71]
	s_waitcnt lgkmcnt(4)
	v_fmamk_f32 v124, v187, 0x3c800000, v221
	v_rsq_f32_e32 v124, v124
	v_add_u32_e32 v127, 0x1800, v113
	v_mul_f32_e32 v142, v142, v124
	v_fma_f32 v142, v120, v142, v121
	v_fmac_f32_e32 v142, v143, v134
	v_mul_f32_e32 v142, v135, v142
	v_bfe_u32 v125, v142, 16, 1
	v_add3_u32 v126, v142, v125, s33
	global_store_short_d16_hi v127, v126, s[70:71]
	s_waitcnt lgkmcnt(3)
	v_fmamk_f32 v124, v188, 0x3c800000, v221
	v_rsq_f32_e32 v124, v124
	v_add_u32_e32 v127, 0x2000, v113
	v_mul_f32_e32 v144, v144, v124
	v_fma_f32 v144, v120, v144, v121
	v_fmac_f32_e32 v144, v145, v192
	v_mul_f32_e32 v144, v193, v144
	v_bfe_u32 v125, v144, 16, 1
	v_add3_u32 v126, v144, v125, s33
	global_store_short_d16_hi v127, v126, s[70:71]
	s_waitcnt lgkmcnt(2)
	v_fmamk_f32 v124, v189, 0x3c800000, v221
	v_rsq_f32_e32 v124, v124
	v_add_u32_e32 v127, 0x2800, v113
	v_mul_f32_e32 v146, v146, v124
	v_fma_f32 v146, v120, v146, v121
	v_fmac_f32_e32 v146, v147, v194
	v_mul_f32_e32 v146, v195, v146
	v_bfe_u32 v125, v146, 16, 1
	v_add3_u32 v126, v146, v125, s33
	global_store_short_d16_hi v127, v126, s[70:71]
	s_waitcnt lgkmcnt(1)
	v_fmamk_f32 v124, v190, 0x3c800000, v221
	v_rsq_f32_e32 v124, v124
	v_add_u32_e32 v127, 0x3000, v113
	v_mul_f32_e32 v148, v148, v124
	v_fma_f32 v148, v120, v148, v121
	v_fmac_f32_e32 v148, v149, v196
	v_mul_f32_e32 v148, v197, v148
	v_bfe_u32 v125, v148, 16, 1
	v_add3_u32 v126, v148, v125, s33
	global_store_short_d16_hi v127, v126, s[70:71]
	s_waitcnt lgkmcnt(0)
	v_fmamk_f32 v124, v191, 0x3c800000, v221
	v_rsq_f32_e32 v124, v124
	v_add_u32_e32 v127, 0x3800, v113
	v_mul_f32_e32 v150, v150, v124
	v_fma_f32 v150, v120, v150, v121
	v_fmac_f32_e32 v150, v151, v198
	v_mul_f32_e32 v150, v199, v150
	v_bfe_u32 v125, v150, 16, 1
	v_add3_u32 v126, v150, v125, s33
	global_store_short_d16_hi v127, v126, s[70:71]
	v_add_u32_e32 v113, 0x4000, v113
	s_add_i32 s1, s1, 1
	s_cmp_eq_u32 s1, 8
	s_cbranch_scc0 .Lm1_sub
	s_add_i32 s2, s2, s58
	s_cmpk_gt_i32 s2, 0x7ff
	s_cbranch_scc0 .LBB0_205
	s_load_dwordx2 s[72:73], s[30:31], 0x118
	v_readlane_b32 s12, v253, 17
	v_readlane_b32 s13, v253, 18
	v_readlane_b32 s67, v255, 14
	v_readlane_b32 s71, v255, 15
	v_readlane_b32 s51, v255, 16
